# stack13 + bf16 residual stream P kept block-permuted like H: phase_prep_x and the residual epilogue store quad-contiguous lines (last FFN2 writes the plain layout for phase_final), residual tile loads
# speedup vs baseline: 1.0182x; 1.0057x over previous
.LBB0_276:
	s_andn2_b64 vcc, exec, s[0:1]
	s_cbranch_vccnz .LBB0_316
	v_and_b32_e32 v236, 15, v2
	v_bfe_u32 v237, v2, 4, 2
	v_lshrrev_b32_e32 v238, 2, v236
	v_lshl_or_b32 v237, v238, 2, v237
	v_and_b32_e32 v236, 3, v236
	v_lshlrev_b32_e32 v236, 3, v236
	v_readlane_b32 s100, v248, 28
	v_and_b32_e32 v240, 63, v2
	v_lshrrev_b32_e32 v241, 4, v240
	v_bfe_u32 v242, v240, 2, 2
	v_sub_u32_e32 v243, 0, v241
	v_and_b32_e32 v243, 3, v243
	v_xor_b32_e32 v242, v242, v243
	v_lshl_or_b32 v241, v241, 2, v242
	v_lshrrev_b32_e32 v243, 7, v2
	v_lshl_or_b32 v241, v243, 4, v241
	v_and_b32_e32 v242, 3, v240
	v_lshlrev_b32_e32 v242, 3, v242
	s_cmp_eq_u32 s100, 7
	s_cselect_b64 s[100:101], -1, 0
	v_and_b32_e32 v240, 15, v2
	v_bfe_u32 v243, v2, 4, 2
	v_lshrrev_b32_e32 v244, 2, v240
	v_sub_u32_e32 v245, 0, v244
	v_and_b32_e32 v245, 3, v245
	v_xor_b32_e32 v243, v243, v245
	v_lshlrev_b32_e32 v244, 8, v244
	v_lshl_or_b32 v243, v243, 6, v244
	v_and_b32_e32 v240, 3, v240
	v_lshl_or_b32 v243, v240, 4, v243
	v_bfe_i32 v4, v2, 27, 1
	v_lshlrev_b32_e32 v3, 4, v2
	v_lshrrev_b32_e32 v4, 22, v4
	v_add_u32_e32 v4, v3, v4
	v_and_b32_e32 v4, 0xfffffc00, v4
	v_ashrrev_i32_e32 v0, 31, v2
	v_sub_u32_e32 v4, v3, v4
	v_lshrrev_b32_e32 v0, 26, v0
	v_lshrrev_b32_e32 v5, 4, v4
	v_add_u32_e32 v0, v2, v0
	v_bitop3_b32 v5, v5, v4, 32 bitop3:0x6c
	v_ashrrev_i32_e32 v4, 31, v4
	v_ashrrev_i32_e32 v0, 6, v0
	v_lshrrev_b32_e32 v4, 26, v4
	v_lshlrev_b32_e32 v6, 3, v0
	v_add_u32_e32 v4, v5, v4
	v_and_b32_e32 v6, -16, v6
	v_ashrrev_i32_e32 v4, 6, v4
	v_lshlrev_b32_e32 v0, 5, v0
	v_add_u32_e32 v6, v4, v6
	v_and_b32_e32 v169, 32, v0
	v_mul_i32_i24_e32 v0, 64, v4
	v_sub_u32_e32 v0, v5, v0
	v_lshlrev_b32_e32 v5, 1, v6
	v_lshrrev_b32_e32 v7, 2, v6
	v_and_b32_e32 v4, 3, v4
	s_mov_b32 s5, 0x7fffffe0
	v_ashrrev_i16_sdwa v0, v152, sext(v0) dst_sel:DWORD dst_unused:UNUSED_PAD src0_sel:DWORD src1_sel:BYTE_0
	v_and_b32_e32 v5, 24, v5
	v_and_b32_e32 v7, 4, v7
	v_and_or_b32 v4, v6, s5, v4
	v_bfe_i32 v170, v0, 0, 16
	v_or3_b32 v4, v4, v7, v5
	v_readlane_b32 s18, v248, 43
	v_add_u32_e32 v0, v169, v170
	v_add_u32_e32 v3, 0x2000, v3
	v_mul_lo_u32 v171, v6, s18
	v_mul_lo_u32 v4, v4, s18
	v_add_lshl_u32 v130, v0, v171, 1
	v_mul_lo_u32 v244, v241, s18
	v_add3_u32 v246, v244, v169, v242
	v_lshlrev_b32_e32 v246, 1, v246
	v_lshl_add_u32 v247, s18, 7, v246
	v_cndmask_b32_e64 v130, v130, v246, s[100:101]
	v_add_lshl_u32 v0, v4, v0, 1
	v_ashrrev_i32_e32 v4, 31, v3
	v_lshrrev_b32_e32 v4, 22, v4
	v_add_u32_e32 v4, v3, v4
	v_ashrrev_i32_e32 v4, 10, v4
	v_mul_i32_i24_e32 v5, 0x400, v4
	v_sub_u32_e32 v3, v3, v5
	v_lshrrev_b32_e32 v5, 4, v3
	v_bitop3_b32 v3, v5, v3, 32 bitop3:0x6c
	v_ashrrev_i32_e32 v6, 31, v3
	v_readlane_b32 s0, v248, 39
	v_lshrrev_b32_e32 v6, 26, v6
	v_readlane_b32 s1, v248, 40
	v_lshlrev_b32_e32 v5, 3, v4
	v_add_u32_e32 v6, v3, v6
	s_lshl_b64 s[0:1], s[0:1], 11
	v_readlane_b32 s6, v251, 7
	v_and_b32_e32 v5, -16, v5
	v_ashrrev_i32_e32 v7, 6, v6
	v_readlane_b32 s7, v251, 8
	s_add_u32 s10, s6, s0
	v_add_u32_e32 v5, v7, v5
	v_lshlrev_b32_e32 v4, 5, v4
	v_and_b32_e32 v7, 3, v7
	s_addc_u32 s11, s7, s1
	v_and_b32_e32 v172, 32, v4
	v_and_b32_e32 v4, 0xc0, v6
	v_and_or_b32 v7, v5, s5, v7
	s_ashr_i32 s5, s4, 8
	s_ashr_i32 s1, s4, 6
	v_sub_u32_e32 v3, v3, v4
	v_lshlrev_b32_e32 v4, 1, v5
	v_lshrrev_b32_e32 v6, 2, v5
	s_lshl_b32 s6, s5, 6
	s_lshl_b32 s7, s3, 8
	s_and_b32 s0, s1, 3
	v_ashrrev_i16_sdwa v3, v152, sext(v3) dst_sel:DWORD dst_unused:UNUSED_PAD src0_sel:DWORD src1_sel:BYTE_0
	v_and_b32_e32 v4, 24, v4
	v_and_b32_e32 v6, 4, v6
	v_and_b32_e32 v148, 15, v2
	s_add_i32 s7, s7, s6
	v_bfe_u32 v149, v2, 4, 2
	v_bfe_i32 v173, v3, 0, 16
	v_or3_b32 v4, v7, v6, v4
	s_lshl_b32 s23, s1, 10
	s_lshl_b32 s1, s0, 5
	v_or_b32_e32 v2, s7, v237
	s_lshl_b32 s7, s2, 8
	v_add_u32_e32 v3, v172, v173
	v_mul_lo_u32 v174, v5, s18
	v_mul_lo_u32 v4, v4, s18
	v_lshlrev_b32_e32 v168, 3, v149
	s_or_b32 s7, s7, s1
	v_or_b32_e32 v8, 16, v2
	v_add_lshl_u32 v132, v3, v174, 1
	v_cndmask_b32_e64 v132, v132, v247, s[100:101]
	v_add_lshl_u32 v134, v4, v3, 1
	v_or_b32_e32 v4, s7, v236
	v_ashrrev_i32_e32 v3, 31, v2
	v_ashrrev_i32_e32 v9, 31, v8
	v_ashrrev_i32_e32 v5, 31, v4
	v_lshlrev_b64 v[6:7], 11, v[2:3]
	v_lshlrev_b64 v[8:9], 11, v[8:9]
	v_lshl_add_u64 v[6:7], s[10:11], 0, v[6:7]
	v_lshlrev_b64 v[4:5], 1, v[4:5]
	v_lshl_add_u64 v[8:9], s[10:11], 0, v[8:9]
	v_lshl_add_u64 v[6:7], v[6:7], 0, v[4:5]
	v_lshl_add_u64 v[8:9], v[8:9], 0, v[4:5]
	global_load_dwordx4 v[62:65], v[6:7], off
	global_load_dwordx4 v[54:57], v[6:7], off offset:256
	global_load_dwordx4 v[58:61], v[8:9], off
	global_load_dwordx4 v[46:49], v[8:9], off offset:256
	v_or_b32_e32 v8, 32, v2
	v_or_b32_e32 v2, 48, v2
	v_ashrrev_i32_e32 v9, 31, v8
	v_ashrrev_i32_e32 v3, 31, v2
	v_lshlrev_b64 v[8:9], 11, v[8:9]
	v_lshlrev_b64 v[2:3], 11, v[2:3]
	v_lshl_add_u64 v[8:9], s[10:11], 0, v[8:9]
	v_lshl_add_u64 v[2:3], s[10:11], 0, v[2:3]
	s_mov_b32 s7, 0x40000
	v_lshl_add_u64 v[8:9], v[8:9], 0, v[4:5]
	v_lshl_add_u64 v[2:3], v[2:3], 0, v[4:5]
	v_add_co_u32_e32 v4, vcc, s7, v6
	s_mov_b64 s[90:91], 0x40000
	s_nop 0
	v_addc_co_u32_e32 v5, vcc, 0, v7, vcc
	s_mov_b32 s7, 0x48000
	global_load_dwordx4 v[50:53], v[8:9], off
	global_load_dwordx4 v[38:41], v[8:9], off offset:256
	global_load_dwordx4 v[42:45], v[2:3], off
	global_load_dwordx4 v[30:33], v[2:3], off offset:256
	v_lshl_add_u64 v[2:3], v[6:7], 0, s[90:91]
	global_load_dwordx4 v[34:37], v[4:5], off
	global_load_dwordx4 v[18:21], v[2:3], off offset:256
	v_add_co_u32_e32 v4, vcc, s7, v6
	s_mov_b64 s[92:93], 0x48000
	s_nop 0
	v_addc_co_u32_e32 v5, vcc, 0, v7, vcc
	s_mov_b32 s7, 0x50000
	v_lshl_add_u64 v[2:3], v[6:7], 0, s[92:93]
	global_load_dwordx4 v[26:29], v[4:5], off
	global_load_dwordx4 v[10:13], v[2:3], off offset:256
	v_add_co_u32_e32 v4, vcc, s7, v6
	s_lshl_b32 s80, s18, 8
	s_mov_b64 s[98:99], 0x50000
	v_addc_co_u32_e32 v5, vcc, 0, v7, vcc
	s_mov_b64 s[8:9], 0x58000
	s_mov_b32 s7, 0x58000
	s_lshl_b64 s[14:15], s[80:81], 1
	v_lshl_add_u64 v[2:3], v[6:7], 0, s[98:99]
	v_lshl_add_u64 v[22:23], v[6:7], 0, s[8:9]
	v_add_co_u32_e32 v6, vcc, s7, v6
	s_ashr_i32 s7, s3, 31
	s_mul_i32 s7, s14, s7
	s_mul_hi_u32 s8, s14, s3
	s_add_i32 s7, s8, s7
	s_bfe_u32 s8, s18, 0x10017
	s_mul_i32 s9, s8, s3
	s_add_i32 s7, s7, s9
	s_ashr_i32 s9, s2, 31
	s_mul_i32 s9, s14, s9
	s_mul_hi_u32 s16, s14, s2
	s_add_i32 s9, s16, s9
	s_mul_i32 s8, s8, s2
	s_add_i32 s9, s9, s8
	s_mul_i32 s8, s14, s2
	v_readlane_b32 s16, v248, 46
	v_readlane_b32 s17, v248, 47
	s_add_u32 s54, s16, s8
	s_addc_u32 s55, s17, s9
	s_add_i32 s58, s23, 0
	v_addc_co_u32_e32 v7, vcc, 0, v7, vcc
	s_add_i32 m0, s58, 0x10000
	s_waitcnt lgkmcnt(0)
	global_load_dwordx4 v[14:17], v[4:5], off
	s_nop 0
	global_load_dwordx4 v[2:5], v[2:3], off offset:256
	s_nop 0
	global_load_dwordx4 v[6:9], v[6:7], off
	s_nop 0
	global_load_dwordx4 v[22:25], v[22:23], off offset:256
	v_mov_b32_e32 v135, v1
	global_load_lds_dwordx4 v0, s[54:55]
	s_add_i32 m0, s58, 0x12000
	s_add_u32 s8, s54, s80
	global_load_lds_dwordx4 v134, s[54:55]
	s_addc_u32 s9, s55, 0
	s_add_i32 m0, s58, 0x14000
	s_mul_i32 s13, s14, s3
	global_load_lds_dwordx4 v0, s[8:9]
	s_add_i32 m0, s58, 0x16000
	v_lshl_add_u64 v[140:141], s[8:9], 0, v[0:1]
	v_lshl_add_u64 v[142:143], s[8:9], 0, v[134:135]
	global_load_lds_dwordx4 v134, s[8:9]
	v_readlane_b32 s8, v248, 48
	v_readlane_b32 s9, v248, 49
	s_add_u32 s56, s8, s13
	s_addc_u32 s57, s9, s7
	s_add_i32 s59, s58, 0x2000
	s_mov_b32 m0, s58
	s_add_u32 s8, s56, s80
	global_load_lds_dwordx4 v130, s[56:57]
	s_mov_b32 m0, s59
	s_addc_u32 s9, s57, 0
	s_add_i32 s60, s58, 0x4000
	global_load_lds_dwordx4 v132, s[56:57]
	s_mov_b32 m0, s60
	s_add_i32 s61, s58, 0x6000
	global_load_lds_dwordx4 v130, s[8:9]
	s_mov_b32 m0, s61
	s_cmp_eq_u32 s5, 1
	global_load_lds_dwordx4 v132, s[8:9]
	v_mov_b32_e32 v131, v1
	v_mov_b32_e32 v133, v1
	s_cselect_b64 s[8:9], -1, 0
	v_lshl_add_u64 v[136:137], s[54:55], 0, v[0:1]
	v_lshl_add_u64 v[138:139], s[54:55], 0, v[134:135]
	v_lshl_add_u64 v[144:145], s[56:57], 0, v[130:131]
	v_lshl_add_u64 v[146:147], s[56:57], 0, v[132:133]
	v_writelane_b32 v248, s8, 29
	s_cmp_lg_u32 s5, 1
	s_nop 0
	v_writelane_b32 v248, s9, 30
	s_cbranch_scc1 .LBB0_279
	s_barrier
.LBB0_279:
	v_readlane_b32 s8, v248, 39
	v_readlane_b32 s9, v248, 40
	s_lshl_b64 s[8:9], s[8:9], 4
	v_readlane_b32 s16, v248, 54
	v_readlane_b32 s17, v248, 55
	s_add_u32 s62, s16, s8
	s_waitcnt vmcnt(0)
	v_lshlrev_b32_e32 v126, 16, v62
	v_and_b32_e32 v127, 0xffff0000, v62
	v_lshlrev_b32_e32 v128, 16, v63
	v_and_b32_e32 v129, 0xffff0000, v63
	v_lshlrev_b32_e32 v114, 16, v64
	v_and_b32_e32 v115, 0xffff0000, v64
	v_lshlrev_b32_e32 v116, 16, v65
	v_and_b32_e32 v117, 0xffff0000, v65
	v_lshlrev_b32_e32 v106, 16, v58
	v_and_b32_e32 v107, 0xffff0000, v58
	v_lshlrev_b32_e32 v108, 16, v59
	v_and_b32_e32 v109, 0xffff0000, v59
	v_lshlrev_b32_e32 v98, 16, v60
	v_and_b32_e32 v99, 0xffff0000, v60
	v_lshlrev_b32_e32 v100, 16, v61
	v_and_b32_e32 v101, 0xffff0000, v61
	v_lshlrev_b32_e32 v58, 16, v34
	v_and_b32_e32 v59, 0xffff0000, v34
	v_lshlrev_b32_e32 v60, 16, v35
	v_and_b32_e32 v61, 0xffff0000, v35
	v_lshlrev_b32_e32 v62, 16, v36
	v_and_b32_e32 v63, 0xffff0000, v36
	v_lshlrev_b32_e32 v64, 16, v37
	v_and_b32_e32 v65, 0xffff0000, v37
	v_lshlrev_b32_e32 v34, 16, v10
	v_and_b32_e32 v35, 0xffff0000, v10
	v_lshlrev_b32_e32 v36, 16, v11
	v_and_b32_e32 v37, 0xffff0000, v11
	s_addc_u32 s63, s17, s9
	s_add_i32 m0, s58, 0x18000
	v_lshl_add_u64 v[10:11], v[136:137], 0, s[94:95]
	s_waitcnt vmcnt(2)
	s_barrier
	global_load_lds_dwordx4 v[10:11], off
	v_lshl_add_u64 v[10:11], v[138:139], 0, s[94:95]
	s_add_i32 m0, s58, 0x1a000
	s_add_i32 s64, s58, 0x8000
	global_load_lds_dwordx4 v[10:11], off
	v_lshl_add_u64 v[10:11], v[144:145], 0, s[94:95]
	s_mov_b32 m0, s64
	s_add_i32 s65, s58, 0xa000
	global_load_lds_dwordx4 v[10:11], off
	v_lshl_add_u64 v[10:11], v[146:147], 0, s[94:95]
	s_mov_b32 m0, s65
	v_or_b32_e32 v146, s6, v148
	global_load_lds_dwordx4 v[10:11], off
	s_add_i32 m0, s58, 0x1c000
	v_lshl_add_u64 v[10:11], v[140:141], 0, s[94:95]
	global_load_lds_dwordx4 v[10:11], off
	v_lshl_add_u64 v[10:11], v[142:143], 0, s[94:95]
	s_add_i32 m0, s58, 0x1e000
	v_lshlrev_b32_e32 v136, 6, v146
	global_load_lds_dwordx4 v[10:11], off
	v_lshlrev_b32_e32 v137, 4, v149
	s_movk_i32 s6, 0x3c0
	v_lshlrev_b32_e32 v138, 2, v146
	s_lshr_b32 s66, s18, 6
	v_and_or_b32 v136, v136, s6, v137
	s_lshl_b32 s5, s5, 13
	v_and_b32_e32 v138, 32, v138
	v_bitop3_b32 v140, v136, s5, v138 bitop3:0xde
	v_lshl_or_b32 v136, v148, 6, v137
	s_lshl_b32 s5, s0, 12
	v_lshlrev_b32_e32 v137, 2, v148
	s_add_i32 s67, s66, -2
	v_and_b32_e32 v137, 32, v137
	s_cmpk_lt_u32 s4, 0x100
	v_readlane_b32 s8, v248, 42
	v_bitop3_b32 v147, v136, s5, v137 bitop3:0xde
	s_cselect_b64 s[20:21], -1, 0
	v_or_b32_e32 v136, s0, v149
	s_lshl_b32 s71, s8, 2
	v_cmp_eq_u32_e64 s[6:7], 0, v136
	v_cvt_f32_u32_e32 v136, s71
	v_add_u32_e32 v148, 0x80, v146
	v_readlane_b32 s8, v249, 45
	s_lshl_b32 s0, s0, 2
	v_rcp_iflag_f32_e32 v136, v136
	v_lshl_add_u32 v164, v146, 4, s8
	v_lshl_add_u32 v166, v148, 4, s8
	v_add_u32_e32 v165, s0, v164
	v_mul_f32_e32 v136, 0x4f7ffffe, v136
	v_cvt_u32_f32_e32 v136, v136
	v_add_u32_e32 v167, s0, v166
	v_or_b32_e32 v168, s1, v168
	s_sub_i32 s0, 0, s71
	v_readfirstlane_b32 s1, v136
	s_waitcnt vmcnt(6)
	v_cmp_eq_u32_e64 s[4:5], 0, v149
	v_or_b32_e32 v149, 16, v146
	v_or_b32_e32 v159, 32, v146
	v_or_b32_e32 v160, 48, v146
	v_add_u32_e32 v161, 0x90, v146
	v_add_u32_e32 v162, 0xa0, v146
	v_add_u32_e32 v163, 0xb0, v146
	s_mul_i32 s0, s0, s1
	v_add_u32_e32 v136, v171, v169
	v_add_u32_e32 v138, v174, v172
	v_lshlrev_b32_e32 v141, 4, v149
	v_lshlrev_b32_e32 v142, 4, v159
	v_lshlrev_b32_e32 v143, 4, v160
	v_lshlrev_b32_e32 v144, 4, v161
	v_lshlrev_b32_e32 v145, 4, v162
	v_lshlrev_b32_e32 v175, 4, v163
	s_mul_hi_u32 s0, s1, s0
	v_add_lshl_u32 v136, v136, v170, 1
	v_cndmask_b32_e64 v136, v136, v246, s[100:101]
	v_mov_b32_e32 v137, v1
	v_add_lshl_u32 v138, v138, v173, 1
	v_cndmask_b32_e64 v138, v138, v247, s[100:101]
	v_mov_b32_e32 v139, v1
	v_lshlrev_b32_e32 v118, 16, v54
	v_and_b32_e32 v119, 0xffff0000, v54
	v_lshlrev_b32_e32 v120, 16, v55
	v_and_b32_e32 v121, 0xffff0000, v55
	v_lshlrev_b32_e32 v122, 16, v56
	v_and_b32_e32 v123, 0xffff0000, v56
	v_lshlrev_b32_e32 v124, 16, v57
	v_and_b32_e32 v125, 0xffff0000, v57
	v_lshlrev_b32_e32 v102, 16, v46
	v_and_b32_e32 v103, 0xffff0000, v46
	v_lshlrev_b32_e32 v104, 16, v47
	v_and_b32_e32 v105, 0xffff0000, v47
	v_lshlrev_b32_e32 v110, 16, v48
	v_and_b32_e32 v111, 0xffff0000, v48
	v_lshlrev_b32_e32 v112, 16, v49
	v_and_b32_e32 v113, 0xffff0000, v49
	v_lshlrev_b32_e32 v90, 16, v50
	v_and_b32_e32 v91, 0xffff0000, v50
	v_lshlrev_b32_e32 v92, 16, v51
	v_and_b32_e32 v93, 0xffff0000, v51
	v_lshlrev_b32_e32 v82, 16, v52
	v_and_b32_e32 v83, 0xffff0000, v52
	v_lshlrev_b32_e32 v84, 16, v53
	v_and_b32_e32 v85, 0xffff0000, v53
	v_lshlrev_b32_e32 v86, 16, v38
	v_and_b32_e32 v87, 0xffff0000, v38
	v_lshlrev_b32_e32 v88, 16, v39
	v_and_b32_e32 v89, 0xffff0000, v39
	v_lshlrev_b32_e32 v94, 16, v40
	v_and_b32_e32 v95, 0xffff0000, v40
	v_lshlrev_b32_e32 v96, 16, v41
	v_and_b32_e32 v97, 0xffff0000, v41
	v_lshlrev_b32_e32 v74, 16, v42
	v_and_b32_e32 v75, 0xffff0000, v42
	v_lshlrev_b32_e32 v76, 16, v43
	v_and_b32_e32 v77, 0xffff0000, v43
	v_lshlrev_b32_e32 v54, 16, v44
	v_and_b32_e32 v55, 0xffff0000, v44
	v_lshlrev_b32_e32 v56, 16, v45
	v_and_b32_e32 v57, 0xffff0000, v45
	v_lshlrev_b32_e32 v70, 16, v30
	v_and_b32_e32 v71, 0xffff0000, v30
	v_lshlrev_b32_e32 v72, 16, v31
	v_and_b32_e32 v73, 0xffff0000, v31
	v_lshlrev_b32_e32 v78, 16, v32
	v_and_b32_e32 v79, 0xffff0000, v32
	v_lshlrev_b32_e32 v80, 16, v33
	v_and_b32_e32 v81, 0xffff0000, v33
	v_lshlrev_b32_e32 v50, 16, v18
	v_and_b32_e32 v51, 0xffff0000, v18
	v_lshlrev_b32_e32 v52, 16, v19
	v_and_b32_e32 v53, 0xffff0000, v19
	v_lshlrev_b32_e32 v66, 16, v20
	v_and_b32_e32 v67, 0xffff0000, v20
	v_lshlrev_b32_e32 v68, 16, v21
	v_and_b32_e32 v69, 0xffff0000, v21
	v_lshlrev_b32_e32 v38, 16, v26
	v_and_b32_e32 v39, 0xffff0000, v26
	v_lshlrev_b32_e32 v40, 16, v27
	v_and_b32_e32 v41, 0xffff0000, v27
	v_lshlrev_b32_e32 v42, 16, v28
	v_and_b32_e32 v43, 0xffff0000, v28
	v_lshlrev_b32_e32 v44, 16, v29
	v_and_b32_e32 v45, 0xffff0000, v29
	v_lshlrev_b32_e32 v46, 16, v12
	v_and_b32_e32 v47, 0xffff0000, v12
	v_lshlrev_b32_e32 v48, 16, v13
	v_and_b32_e32 v49, 0xffff0000, v13
	v_lshlrev_b32_e32 v18, 16, v14
	v_and_b32_e32 v19, 0xffff0000, v14
	v_lshlrev_b32_e32 v20, 16, v15
	v_and_b32_e32 v21, 0xffff0000, v15
	v_lshlrev_b32_e32 v26, 16, v16
	v_and_b32_e32 v27, 0xffff0000, v16
	v_lshlrev_b32_e32 v28, 16, v17
	v_and_b32_e32 v29, 0xffff0000, v17
	v_lshlrev_b32_e32 v14, 16, v2
	v_and_b32_e32 v15, 0xffff0000, v2
	v_lshlrev_b32_e32 v16, 16, v3
	v_and_b32_e32 v17, 0xffff0000, v3
	v_lshlrev_b32_e32 v30, 16, v4
	v_and_b32_e32 v31, 0xffff0000, v4
	v_lshlrev_b32_e32 v32, 16, v5
	v_and_b32_e32 v33, 0xffff0000, v5
	v_lshlrev_b32_e32 v2, 16, v6
	v_and_b32_e32 v3, 0xffff0000, v6
	v_lshlrev_b32_e32 v4, 16, v7
	v_and_b32_e32 v5, 0xffff0000, v7
	v_lshlrev_b32_e32 v6, 16, v8
	v_and_b32_e32 v7, 0xffff0000, v8
	v_lshlrev_b32_e32 v8, 16, v9
	v_and_b32_e32 v9, 0xffff0000, v9
	v_lshlrev_b32_e32 v10, 16, v22
	v_and_b32_e32 v11, 0xffff0000, v22
	v_lshlrev_b32_e32 v12, 16, v23
	v_and_b32_e32 v13, 0xffff0000, v23
	v_lshlrev_b32_e32 v22, 16, v24
	v_and_b32_e32 v23, 0xffff0000, v24
	v_lshlrev_b32_e32 v24, 16, v25
	v_and_b32_e32 v25, 0xffff0000, v25
	s_mov_b32 s70, 0
	s_mov_b32 s13, s81
	s_lshr_b32 s96, s12, 3
	s_add_i32 s97, s1, s0
	v_lshl_add_u64 v[136:137], s[80:81], 0, v[136:137]
	v_lshl_add_u64 v[138:139], s[80:81], 0, v[138:139]
	v_add_u32_e32 v169, 0, v140
	v_lshrrev_b32_e32 v245, 10, v169
	v_lshl_or_b32 v245, v245, 10, v243
	v_cndmask_b32_e64 v169, v169, v245, s[100:101]
	v_readlane_b32 s100, v248, 24
	s_nop 0
	s_and_b32 s100, s100, 0xffff
	s_cmpk_lg_u32 s100, 0x307
	s_cselect_b64 s[100:101], -1, 0
	v_add_u32_e32 v170, s8, v141
	v_add_u32_e32 v171, s8, v142
	v_add_u32_e32 v172, s8, v143
	v_add_u32_e32 v173, s8, v144
	v_add_u32_e32 v174, s8, v145
	v_add_u32_e32 v175, s8, v175
	s_barrier
	s_branch .LBB0_282

.LBB0_293:
	v_cvt_pk_bf16_f32 v176, v126, v127
	v_mul_f32_e32 v127, v127, v127
	v_fmac_f32_e32 v127, v126, v126
	v_mul_f32_e32 v126, v119, v119
	v_fmac_f32_e32 v126, v118, v118
	v_fmac_f32_e32 v127, v128, v128
	v_fmac_f32_e32 v126, v120, v120
	v_fmac_f32_e32 v127, v129, v129
	v_fmac_f32_e32 v126, v121, v121
	v_fmac_f32_e32 v127, v114, v114
	v_fmac_f32_e32 v126, v122, v122
	v_fmac_f32_e32 v127, v115, v115
	v_fmac_f32_e32 v126, v123, v123
	v_fmac_f32_e32 v127, v116, v116
	v_fmac_f32_e32 v126, v124, v124
	v_cvt_pk_bf16_f32 v177, v128, v129
	v_fmac_f32_e32 v127, v117, v117
	v_fmac_f32_e32 v126, v125, v125
	v_and_b32_e32 v128, 64, v158
	v_add_f32_e32 v127, v127, v126
	v_xor_b32_e32 v126, 16, v158
	v_add_u32_e32 v128, 64, v128
	v_cmp_lt_i32_e32 vcc, v126, v128
	v_cvt_pk_bf16_f32 v178, v114, v115
	v_xor_b32_e32 v114, 32, v158
	s_lshl_b32 s18, s3, 8
	v_cndmask_b32_e32 v126, v158, v126, vcc
	v_lshlrev_b32_e32 v126, 2, v126
	ds_bpermute_b32 v129, v126, v127
	v_cmp_lt_i32_e32 vcc, v114, v128
	v_and_b32_e32 v236, 15, v150
	v_bfe_u32 v237, v150, 4, 2
	v_lshrrev_b32_e32 v238, 2, v236
	v_lshl_or_b32 v237, v238, 2, v237
	v_and_b32_e32 v236, 3, v236
	v_lshlrev_b32_e32 v236, 3, v236
	v_and_or_b32 v238, v146, -16, v237
	v_lshrrev_b32_e32 v239, 5, v168
	v_lshl_or_b32 v239, v239, 5, v236
	v_cndmask_b32_e64 v238, v146, v238, s[100:101]
	v_cndmask_b32_e64 v239, v168, v239, s[100:101]
	v_add_u32_e32 v140, s18, v238
	v_cvt_pk_bf16_f32 v179, v116, v117
	v_ashrrev_i32_e32 v141, 31, v140
	v_cndmask_b32_e32 v114, v158, v114, vcc
	s_waitcnt lgkmcnt(0)
	v_add_f32_e32 v115, v127, v129
	v_lshlrev_b32_e32 v114, 2, v114
	ds_bpermute_b32 v116, v114, v115
	v_lshl_or_b32 v144, s2, 8, v239
	v_lshlrev_b64 v[142:143], 11, v[140:141]
	v_ashrrev_i32_e32 v145, 31, v144
	v_lshl_add_u64 v[142:143], s[10:11], 0, v[142:143]
	v_lshl_add_u64 v[142:143], v[144:145], 1, v[142:143]
	global_store_dwordx4 v[142:143], v[176:179], off
	v_cvt_pk_bf16_f32 v118, v118, v119
	v_cvt_pk_bf16_f32 v119, v120, v121
	v_cvt_pk_bf16_f32 v120, v122, v123
	v_cvt_pk_bf16_f32 v121, v124, v125
	global_store_dwordx4 v[142:143], v[118:121], off offset:256
	s_and_saveexec_b64 s[54:55], s[4:5]
	s_cbranch_execz .LBB0_295
	s_waitcnt lgkmcnt(0)
	v_add_f32_e32 v115, v115, v116
	ds_write_b32 v165, v115

.LBB0_309:
	s_or_b64 exec, exec, s[54:55]
	s_waitcnt lgkmcnt(0)
	s_barrier
	s_and_saveexec_b64 s[54:55], s[6:7]
	s_cbranch_execz .LBB0_311
	s_waitcnt lgkmcnt(0)
	ds_read_b128 v[2:5], v164
	s_ashr_i32 s3, s2, 31
	s_lshl_b64 s[2:3], s[2:3], 2
	s_add_u32 s2, s62, s2
	s_addc_u32 s3, s63, s3
	s_waitcnt lgkmcnt(0)
	v_add_f32_e32 v2, v2, v3
	v_add_f32_e32 v3, v4, v5
	v_add_f32_e32 v4, v2, v3
	v_add_u32_e32 v236, s18, v146
	v_ashrrev_i32_e32 v237, 31, v236
	v_lshl_add_u64 v[2:3], v[236:237], 4, s[2:3]
	global_store_dword v[2:3], v4, off
	ds_read_b128 v[2:5], v170
	s_waitcnt lgkmcnt(0)
	v_add_f32_e32 v2, v2, v3
	v_add_f32_e32 v3, v4, v5
	v_add_f32_e32 v4, v2, v3
	v_add_u32_e32 v2, s18, v149
	v_ashrrev_i32_e32 v3, 31, v2
	v_lshl_add_u64 v[2:3], v[2:3], 4, s[2:3]
	global_store_dword v[2:3], v4, off
	ds_read_b128 v[2:5], v171
	s_waitcnt lgkmcnt(0)
	v_add_f32_e32 v2, v2, v3
	v_add_f32_e32 v3, v4, v5
	v_add_f32_e32 v4, v2, v3
	v_add_u32_e32 v2, s18, v159
	v_ashrrev_i32_e32 v3, 31, v2
	v_lshl_add_u64 v[2:3], v[2:3], 4, s[2:3]
	global_store_dword v[2:3], v4, off
	ds_read_b128 v[2:5], v172
	s_waitcnt lgkmcnt(0)
	v_add_f32_e32 v2, v2, v3
	v_add_f32_e32 v3, v4, v5
	v_add_f32_e32 v4, v2, v3
	v_add_u32_e32 v2, s18, v160
	v_ashrrev_i32_e32 v3, 31, v2
	v_lshl_add_u64 v[2:3], v[2:3], 4, s[2:3]
	global_store_dword v[2:3], v4, off
	ds_read_b128 v[2:5], v166
	s_waitcnt lgkmcnt(0)
	v_add_f32_e32 v2, v2, v3
	v_add_f32_e32 v3, v4, v5
	v_add_f32_e32 v4, v2, v3
	v_add_u32_e32 v2, s18, v148
	v_ashrrev_i32_e32 v3, 31, v2
	v_lshl_add_u64 v[2:3], v[2:3], 4, s[2:3]
	global_store_dword v[2:3], v4, off
	ds_read_b128 v[2:5], v173
	s_waitcnt lgkmcnt(0)
	v_add_f32_e32 v2, v2, v3
	v_add_f32_e32 v3, v4, v5
	v_add_f32_e32 v4, v2, v3
	v_add_u32_e32 v2, s18, v161
	v_ashrrev_i32_e32 v3, 31, v2
	v_lshl_add_u64 v[2:3], v[2:3], 4, s[2:3]
	global_store_dword v[2:3], v4, off
	ds_read_b128 v[2:5], v174
	s_waitcnt lgkmcnt(0)
	v_add_f32_e32 v2, v2, v3
	v_add_f32_e32 v3, v4, v5
	v_add_f32_e32 v4, v2, v3
	v_add_u32_e32 v2, s18, v162
	v_ashrrev_i32_e32 v3, 31, v2
	v_lshl_add_u64 v[2:3], v[2:3], 4, s[2:3]
	global_store_dword v[2:3], v4, off
	ds_read_b128 v[2:5], v175
	s_waitcnt lgkmcnt(0)
	v_add_f32_e32 v2, v2, v3
	v_add_f32_e32 v3, v4, v5
	v_add_f32_e32 v4, v2, v3
	v_add_u32_e32 v2, s18, v163
	v_ashrrev_i32_e32 v3, 31, v2
	v_lshl_add_u64 v[2:3], v[2:3], 4, s[2:3]
	global_store_dword v[2:3], v4, off
.LBB0_311:
	s_or_b64 exec, exec, s[54:55]
	s_and_b64 vcc, exec, s[8:9]
	s_mov_b64 s[2:3], -1
	s_cbranch_vccnz .LBB0_281
	v_and_b32_e32 v236, 15, v150
	v_bfe_u32 v237, v150, 4, 2
	v_lshrrev_b32_e32 v238, 2, v236
	v_lshl_or_b32 v237, v238, 2, v237
	v_and_b32_e32 v236, 3, v236
	v_lshlrev_b32_e32 v236, 3, v236
	v_and_or_b32 v238, v146, -16, v237
	v_lshrrev_b32_e32 v239, 5, v168
	v_lshl_or_b32 v239, v239, 5, v236
	v_lshl_add_u32 v2, s17, 8, v238
	v_or_b32_e32 v8, 16, v2
	v_lshl_or_b32 v4, s16, 8, v239
	s_waitcnt lgkmcnt(0)
	v_ashrrev_i32_e32 v3, 31, v2
	v_ashrrev_i32_e32 v9, 31, v8
	v_ashrrev_i32_e32 v5, 31, v4
	v_lshlrev_b64 v[6:7], 11, v[2:3]
	v_lshlrev_b64 v[8:9], 11, v[8:9]
	v_lshl_add_u64 v[6:7], s[10:11], 0, v[6:7]
	v_lshlrev_b64 v[4:5], 1, v[4:5]
	v_lshl_add_u64 v[8:9], s[10:11], 0, v[8:9]
	v_lshl_add_u64 v[6:7], v[6:7], 0, v[4:5]
	v_lshl_add_u64 v[8:9], v[8:9], 0, v[4:5]
	global_load_dwordx4 v[62:65], v[6:7], off
	global_load_dwordx4 v[54:57], v[6:7], off offset:256
	global_load_dwordx4 v[58:61], v[8:9], off
	global_load_dwordx4 v[46:49], v[8:9], off offset:256
	v_or_b32_e32 v8, 32, v2
	v_or_b32_e32 v2, 48, v2
	v_ashrrev_i32_e32 v9, 31, v8
	v_ashrrev_i32_e32 v3, 31, v2
	v_lshlrev_b64 v[8:9], 11, v[8:9]
	v_lshlrev_b64 v[2:3], 11, v[2:3]
	v_lshl_add_u64 v[8:9], s[10:11], 0, v[8:9]
	v_lshl_add_u64 v[2:3], s[10:11], 0, v[2:3]
	s_mov_b32 s2, 0x40000
	v_lshl_add_u64 v[8:9], v[8:9], 0, v[4:5]
	v_lshl_add_u64 v[2:3], v[2:3], 0, v[4:5]
	v_add_co_u32_e32 v4, vcc, s2, v6
	s_mov_b32 s2, 0x48000
	s_nop 0
	v_addc_co_u32_e32 v5, vcc, 0, v7, vcc
	global_load_dwordx4 v[50:53], v[8:9], off
	global_load_dwordx4 v[38:41], v[8:9], off offset:256
	global_load_dwordx4 v[42:45], v[2:3], off
	global_load_dwordx4 v[30:33], v[2:3], off offset:256
	v_lshl_add_u64 v[2:3], v[6:7], 0, s[90:91]
	global_load_dwordx4 v[34:37], v[4:5], off
	global_load_dwordx4 v[18:21], v[2:3], off offset:256
	v_add_co_u32_e32 v4, vcc, s2, v6
	v_lshl_add_u64 v[2:3], v[6:7], 0, s[92:93]
	s_nop 0
	v_addc_co_u32_e32 v5, vcc, 0, v7, vcc
	global_load_dwordx4 v[26:29], v[4:5], off
	global_load_dwordx4 v[10:13], v[2:3], off offset:256
	v_add_co_u32_e32 v4, vcc, 0x50000, v6
	s_mov_b64 s[2:3], 0x58000
	s_nop 0
	v_addc_co_u32_e32 v5, vcc, 0, v7, vcc
	v_lshl_add_u64 v[2:3], v[6:7], 0, s[98:99]
	v_lshl_add_u64 v[22:23], v[6:7], 0, s[2:3]
	v_add_co_u32_e32 v6, vcc, 0x58000, v6
	global_load_dwordx4 v[14:17], v[4:5], off
	s_nop 0
	global_load_dwordx4 v[2:5], v[2:3], off offset:256
	v_addc_co_u32_e32 v7, vcc, 0, v7, vcc
	global_load_dwordx4 v[6:9], v[6:7], off
	s_nop 0
	global_load_dwordx4 v[22:25], v[22:23], off offset:256
	v_readlane_b32 s2, v248, 29
	v_readlane_b32 s3, v248, 30
	s_andn2_b64 vcc, exec, s[2:3]
	s_cbranch_vccnz .LBB0_280
	s_barrier
	s_branch .LBB0_280

.LBB0_321:
	v_bfe_i32 v4, v2, 27, 1
	v_lshlrev_b32_e32 v3, 4, v2
	v_lshrrev_b32_e32 v4, 22, v4
	v_add_u32_e32 v4, v3, v4
	v_and_b32_e32 v4, 0xfffffc00, v4
	v_ashrrev_i32_e32 v0, 31, v2
	v_sub_u32_e32 v4, v3, v4
	v_lshrrev_b32_e32 v0, 26, v0
	v_lshrrev_b32_e32 v5, 4, v4
	v_add_u32_e32 v0, v2, v0
	v_bitop3_b32 v5, v5, v4, 32 bitop3:0x6c
	v_ashrrev_i32_e32 v4, 31, v4
	v_ashrrev_i32_e32 v0, 6, v0
	v_lshrrev_b32_e32 v4, 26, v4
	v_lshlrev_b32_e32 v6, 3, v0
	v_add_u32_e32 v4, v5, v4
	v_and_b32_e32 v6, -16, v6
	v_ashrrev_i32_e32 v4, 6, v4
	v_lshlrev_b32_e32 v0, 5, v0
	v_add_u32_e32 v6, v4, v6
	v_and_b32_e32 v14, 32, v0
	v_mul_i32_i24_e32 v0, 64, v4
	v_sub_u32_e32 v0, v5, v0
	v_lshlrev_b32_e32 v5, 1, v6
	v_lshrrev_b32_e32 v7, 2, v6
	v_and_b32_e32 v4, 3, v4
	s_mov_b32 s2, 0x7fffffe0
	v_ashrrev_i16_sdwa v0, v152, sext(v0) dst_sel:DWORD dst_unused:UNUSED_PAD src0_sel:DWORD src1_sel:BYTE_0
	v_and_b32_e32 v5, 24, v5
	v_and_b32_e32 v7, 4, v7
	v_and_or_b32 v4, v6, s2, v4
	v_bfe_i32 v15, v0, 0, 16
	v_or3_b32 v4, v4, v7, v5
	v_readlane_b32 s15, v248, 43
	v_add_u32_e32 v0, v14, v15
	v_add_u32_e32 v3, 0x2000, v3
	v_mul_lo_u32 v16, v6, s15
	v_mul_lo_u32 v4, v4, s15
	v_add_lshl_u32 v130, v0, v16, 1
	v_and_b32_e32 v240, 63, v150
	v_lshrrev_b32_e32 v241, 4, v240
	v_bfe_u32 v242, v240, 2, 2
	v_sub_u32_e32 v243, 0, v241
	v_and_b32_e32 v243, 3, v243
	v_xor_b32_e32 v242, v242, v243
	v_lshl_or_b32 v241, v241, 2, v242
	v_lshrrev_b32_e32 v243, 7, v150
	v_lshl_or_b32 v241, v243, 4, v241
	v_and_b32_e32 v242, 3, v240
	v_lshlrev_b32_e32 v242, 3, v242
	v_mul_lo_u32 v244, v241, s15
	v_add3_u32 v246, v244, v14, v242
	v_lshlrev_b32_e32 v246, 1, v246
	v_lshl_add_u32 v247, s15, 7, v246
	v_mov_b32_e32 v130, v246
	v_and_b32_e32 v240, 15, v150
	v_bfe_u32 v243, v150, 4, 2
	v_lshrrev_b32_e32 v244, 2, v240
	v_sub_u32_e32 v245, 0, v244
	v_and_b32_e32 v245, 3, v245
	v_xor_b32_e32 v243, v243, v245
	v_lshlrev_b32_e32 v244, 8, v244
	v_lshl_or_b32 v243, v243, 6, v244
	v_and_b32_e32 v240, 3, v240
	v_lshl_or_b32 v243, v240, 4, v243
	v_add_lshl_u32 v0, v4, v0, 1
	v_ashrrev_i32_e32 v4, 31, v3
	v_lshrrev_b32_e32 v4, 22, v4
	v_add_u32_e32 v4, v3, v4
	v_ashrrev_i32_e32 v4, 10, v4
	v_mul_i32_i24_e32 v5, 0x400, v4
	v_sub_u32_e32 v3, v3, v5
	v_lshrrev_b32_e32 v5, 4, v3
	v_bitop3_b32 v3, v5, v3, 32 bitop3:0x6c
	v_ashrrev_i32_e32 v6, 31, v3
	v_lshrrev_b32_e32 v6, 26, v6
	v_lshlrev_b32_e32 v5, 3, v4
	v_add_u32_e32 v6, v3, v6
	v_and_b32_e32 v5, -16, v5
	v_ashrrev_i32_e32 v7, 6, v6
	v_lshlrev_b32_e32 v4, 5, v4
	v_add_u32_e32 v5, v7, v5
	v_and_b32_e32 v17, 32, v4
	v_and_b32_e32 v4, 0xc0, v6
	s_ashr_i32 s10, s0, 8
	s_ashr_i32 s6, s0, 6
	v_bfe_u32 v22, v2, 4, 2
	v_sub_u32_e32 v3, v3, v4
	v_lshlrev_b32_e32 v4, 1, v5
	v_lshrrev_b32_e32 v6, 2, v5
	v_and_b32_e32 v7, 3, v7
	s_lshl_b32 s7, s10, 6
	s_lshl_b32 s8, s62, 8
	s_sext_i32_i16 s63, s1
	s_and_b32 s1, s6, 3
	v_ashrrev_i16_sdwa v3, v152, sext(v3) dst_sel:DWORD dst_unused:UNUSED_PAD src0_sel:DWORD src1_sel:BYTE_0
	v_and_b32_e32 v4, 24, v4
	v_and_b32_e32 v6, 4, v6
	v_and_or_b32 v7, v5, s2, v7
	v_and_b32_e32 v20, 15, v2
	s_lshl_b32 s35, s6, 10
	v_lshlrev_b32_e32 v21, 4, v22
	s_lshl_b32 s6, s10, 13
	s_add_i32 s8, s8, s7
	v_bfe_i32 v18, v3, 0, 16
	v_or3_b32 v4, v7, v6, v4
	v_or3_b32 v2, s8, v21, v20
	s_lshl_b32 s8, s1, 11
	s_add_i32 s9, s6, 0
	v_add_u32_e32 v3, v17, v18
	v_mul_lo_u32 v19, v5, s15
	v_mul_lo_u32 v4, v4, s15
	s_add_i32 s8, s9, s8
	v_add_lshl_u32 v132, v3, v19, 1
	v_mov_b32_e32 v132, v247
	v_add_lshl_u32 v134, v4, v3, 1
	v_ashrrev_i32_e32 v3, 31, v2
	s_add_i32 s18, s8, 0x21010
	s_lshl_b32 s80, s15, 8
	v_lshl_add_u64 v[2:3], v[2:3], 4, s[96:97]
	s_mov_b32 m0, s18
	s_lshl_b64 s[2:3], s[80:81], 1
	global_load_lds_dwordx4 v[2:3], off
	s_add_i32 m0, s8, 0x21410
	s_ashr_i32 s8, s62, 31
	s_mul_i32 s8, s2, s8
	s_mul_hi_u32 s9, s2, s62
	s_add_i32 s8, s9, s8
	s_bfe_u32 s9, s15, 0x10017
	s_mul_i32 s11, s9, s62
	s_add_i32 s11, s8, s11
	s_ashr_i32 s8, s63, 31
	s_mul_i32 s8, s2, s8
	s_mul_hi_u32 s14, s2, s63
	s_add_i32 s8, s14, s8
	s_mul_i32 s9, s9, s63
	s_add_i32 s8, s8, s9
	s_mul_i32 s9, s2, s63
	s_mov_b64 s[16:17], 0x800
	s_add_u32 s20, s90, s9
	v_lshl_add_u64 v[2:3], v[2:3], 0, s[16:17]
	s_addc_u32 s21, s91, s8
	s_add_i32 s19, s35, 0
	global_load_lds_dwordx4 v[2:3], off
	s_add_i32 m0, s19, 0x10000
	s_mul_i32 s13, s2, s62
	global_load_lds_dwordx4 v0, s[20:21]
	s_add_i32 m0, s19, 0x12000
	s_add_u32 s8, s20, s80
	global_load_lds_dwordx4 v134, s[20:21]
	s_addc_u32 s9, s21, 0
	s_add_i32 m0, s19, 0x14000
	v_mov_b32_e32 v135, v1
	global_load_lds_dwordx4 v0, s[8:9]
	s_add_i32 m0, s19, 0x16000
	s_add_u32 s16, s92, s13
	s_addc_u32 s17, s93, s11
	s_add_i32 s29, s19, 0x2000
	v_lshl_add_u64 v[6:7], s[8:9], 0, v[0:1]
	v_lshl_add_u64 v[8:9], s[8:9], 0, v[134:135]
	global_load_lds_dwordx4 v134, s[8:9]
	s_mov_b32 m0, s19
	s_add_u32 s8, s16, s80
	global_load_lds_dwordx4 v130, s[16:17]
	s_mov_b32 m0, s29
	s_addc_u32 s9, s17, 0
	s_add_i32 s30, s19, 0x4000
	global_load_lds_dwordx4 v132, s[16:17]
	s_mov_b32 m0, s30
	s_add_i32 s31, s19, 0x6000
	global_load_lds_dwordx4 v130, s[8:9]
	s_mov_b32 m0, s31
	v_mov_b32_e32 v131, v1
	global_load_lds_dwordx4 v132, s[8:9]
	v_mov_b32_e32 v133, v1
	s_cmp_eq_u32 s10, 1
	v_lshl_add_u64 v[2:3], s[20:21], 0, v[0:1]
	v_lshl_add_u64 v[4:5], s[20:21], 0, v[134:135]
	v_lshl_add_u64 v[10:11], s[16:17], 0, v[130:131]
	v_lshl_add_u64 v[12:13], s[16:17], 0, v[132:133]
	s_cselect_b64 s[8:9], -1, 0
	s_cmp_lg_u32 s10, 1
	s_cbranch_scc1 .LBB0_323
	s_barrier
.LBB0_323:
	s_add_i32 m0, s19, 0x18000
	v_lshl_add_u64 v[2:3], v[2:3], 0, s[94:95]
	s_waitcnt vmcnt(2)
	s_barrier
	global_load_lds_dwordx4 v[2:3], off
	v_lshl_add_u64 v[2:3], v[4:5], 0, s[94:95]
	s_add_i32 m0, s19, 0x1a000
	s_add_i32 s56, s19, 0x8000
	global_load_lds_dwordx4 v[2:3], off
	v_lshl_add_u64 v[2:3], v[10:11], 0, s[94:95]
	s_mov_b32 m0, s56
	s_add_i32 s57, s19, 0xa000
	global_load_lds_dwordx4 v[2:3], off
	v_lshl_add_u64 v[2:3], v[12:13], 0, s[94:95]
	s_mov_b32 m0, s57
	v_or_b32_e32 v142, s7, v20
	global_load_lds_dwordx4 v[2:3], off
	s_add_i32 m0, s19, 0x1c000
	v_lshl_add_u64 v[2:3], v[6:7], 0, s[94:95]
	global_load_lds_dwordx4 v[2:3], off
	v_lshl_add_u64 v[2:3], v[8:9], 0, s[94:95]
	s_add_i32 m0, s19, 0x1e000
	v_lshlrev_b32_e32 v23, 6, v142
	global_load_lds_dwordx4 v[2:3], off
	s_movk_i32 s7, 0x3c0
	v_lshlrev_b32_e32 v24, 2, v142
	v_add_u32_e32 v2, v16, v14
	s_lshr_b32 s55, s15, 6
	v_and_or_b32 v23, v23, s7, v21
	v_and_b32_e32 v24, 32, v24
	v_add_lshl_u32 v2, v2, v15, 1
	v_mov_b32_e32 v2, v246
	v_mov_b32_e32 v3, v1
	v_bitop3_b32 v23, v23, s6, v24 bitop3:0xde
	s_lshl_b32 s6, s1, 12
	v_lshlrev_b32_e32 v25, 2, v20
	s_waitcnt vmcnt(6)
	s_add_i32 s58, s55, -2
	v_lshl_add_u64 v[136:137], s[80:81], 0, v[2:3]
	v_add_u32_e32 v2, v19, v17
	v_lshlrev_b32_e32 v22, 3, v22
	v_lshl_or_b32 v24, v20, 6, v21
	v_and_b32_e32 v25, 32, v25
	s_cmpk_lt_u32 s0, 0x100
	v_lshlrev_b32_e32 v4, 4, v20
	v_add_lshl_u32 v2, v2, v18, 1
	v_mov_b32_e32 v2, v247
	v_bitop3_b32 v143, v24, s6, v25 bitop3:0xde
	v_lshl_or_b32 v144, s1, 5, v22
	v_or_b32_e32 v145, v142, v21
	s_cselect_b64 s[10:11], -1, 0
	s_mov_b32 s13, s81
	v_lshl_add_u64 v[138:139], s[80:81], 0, v[2:3]
	s_mov_b32 s59, 0
	v_add_u32_e32 v146, 0, v23
	v_lshrrev_b32_e32 v245, 10, v146
	v_lshl_or_b32 v146, v245, 10, v243
	v_add_u32_e32 v147, s18, v4
	s_barrier
	s_branch .LBB0_326

.LBB0_346:
	s_andn2_b64 vcc, exec, s[0:1]
	s_cbranch_vccnz .LBB0_401
	v_bfe_i32 v4, v2, 27, 1
	s_waitcnt lgkmcnt(0)
	v_lshlrev_b32_e32 v3, 4, v2
	v_lshrrev_b32_e32 v4, 22, v4
	v_add_u32_e32 v4, v3, v4
	v_and_b32_e32 v4, 0xfffffc00, v4
	v_ashrrev_i32_e32 v0, 31, v2
	v_sub_u32_e32 v4, v3, v4
	v_lshrrev_b32_e32 v0, 26, v0
	v_lshrrev_b32_e32 v5, 4, v4
	v_add_u32_e32 v0, v2, v0
	v_bitop3_b32 v5, v5, v4, 32 bitop3:0x6c
	v_ashrrev_i32_e32 v4, 31, v4
	v_ashrrev_i32_e32 v0, 6, v0
	v_lshrrev_b32_e32 v4, 26, v4
	v_lshlrev_b32_e32 v6, 3, v0
	v_add_u32_e32 v4, v5, v4
	v_and_b32_e32 v6, -16, v6
	v_ashrrev_i32_e32 v4, 6, v4
	v_lshlrev_b32_e32 v0, 5, v0
	v_add_u32_e32 v6, v4, v6
	v_and_b32_e32 v14, 32, v0
	v_mul_i32_i24_e32 v0, 64, v4
	v_sub_u32_e32 v0, v5, v0
	v_lshlrev_b32_e32 v5, 1, v6
	v_lshrrev_b32_e32 v7, 2, v6
	v_and_b32_e32 v4, 3, v4
	s_mov_b32 s2, 0x7fffffe0
	v_ashrrev_i16_sdwa v0, v152, sext(v0) dst_sel:DWORD dst_unused:UNUSED_PAD src0_sel:DWORD src1_sel:BYTE_0
	v_and_b32_e32 v5, 24, v5
	v_and_b32_e32 v7, 4, v7
	v_and_or_b32 v4, v6, s2, v4
	v_bfe_i32 v15, v0, 0, 16
	v_or3_b32 v4, v4, v7, v5
	v_readlane_b32 s13, v248, 43
	v_add_u32_e32 v0, v14, v15
	v_add_u32_e32 v3, 0x2000, v3
	v_mul_lo_u32 v16, v6, s13
	v_mul_lo_u32 v4, v4, s13
	v_add_lshl_u32 v130, v0, v16, 1
	v_and_b32_e32 v240, 63, v150
	v_lshrrev_b32_e32 v241, 4, v240
	v_bfe_u32 v242, v240, 2, 2
	v_sub_u32_e32 v243, 0, v241
	v_and_b32_e32 v243, 3, v243
	v_xor_b32_e32 v242, v242, v243
	v_lshl_or_b32 v241, v241, 2, v242
	v_lshrrev_b32_e32 v243, 7, v150
	v_lshl_or_b32 v241, v243, 4, v241
	v_and_b32_e32 v242, 3, v240
	v_lshlrev_b32_e32 v242, 3, v242
	v_mul_lo_u32 v244, v241, s13
	v_add3_u32 v246, v244, v14, v242
	v_lshlrev_b32_e32 v246, 1, v246
	v_lshl_add_u32 v247, s13, 7, v246
	v_mov_b32_e32 v130, v246
	v_and_b32_e32 v240, 15, v150
	v_bfe_u32 v243, v150, 4, 2
	v_lshrrev_b32_e32 v244, 2, v240
	v_sub_u32_e32 v245, 0, v244
	v_and_b32_e32 v245, 3, v245
	v_xor_b32_e32 v243, v243, v245
	v_lshlrev_b32_e32 v244, 8, v244
	v_lshl_or_b32 v243, v243, 6, v244
	v_and_b32_e32 v240, 3, v240
	v_lshl_or_b32 v243, v240, 4, v243
	v_add_lshl_u32 v0, v4, v0, 1
	v_ashrrev_i32_e32 v4, 31, v3
	v_lshrrev_b32_e32 v4, 22, v4
	v_add_u32_e32 v4, v3, v4
	v_ashrrev_i32_e32 v4, 10, v4
	v_mul_i32_i24_e32 v5, 0x400, v4
	v_sub_u32_e32 v3, v3, v5
	v_lshrrev_b32_e32 v5, 4, v3
	v_bitop3_b32 v3, v5, v3, 32 bitop3:0x6c
	v_ashrrev_i32_e32 v6, 31, v3
	v_lshrrev_b32_e32 v6, 26, v6
	v_lshlrev_b32_e32 v5, 3, v4
	v_add_u32_e32 v6, v3, v6
	v_and_b32_e32 v5, -16, v5
	v_ashrrev_i32_e32 v7, 6, v6
	v_lshlrev_b32_e32 v4, 5, v4
	v_add_u32_e32 v5, v7, v5
	v_and_b32_e32 v17, 32, v4
	v_and_b32_e32 v4, 0xc0, v6
	v_and_b32_e32 v7, 3, v7
	s_ashr_i32 s8, s4, 8
	s_ashr_i32 s1, s4, 6
	v_bfe_u32 v20, v2, 4, 2
	v_sub_u32_e32 v3, v3, v4
	v_lshlrev_b32_e32 v4, 1, v5
	v_lshrrev_b32_e32 v6, 2, v5
	v_and_or_b32 v7, v5, s2, v7
	s_lshl_b32 s5, s8, 6
	s_lshl_b32 s2, s18, 8
	s_and_b32 s0, s1, 3
	v_ashrrev_i16_sdwa v3, v152, sext(v3) dst_sel:DWORD dst_unused:UNUSED_PAD src0_sel:DWORD src1_sel:BYTE_0
	v_and_b32_e32 v4, 24, v4
	v_and_b32_e32 v6, 4, v6
	v_and_b32_e32 v21, 15, v2
	s_lshl_b32 s20, s1, 10
	v_lshlrev_b32_e32 v22, 4, v20
	s_lshl_b32 s1, s8, 13
	s_add_i32 s2, s2, s5
	v_bfe_i32 v18, v3, 0, 16
	v_or3_b32 v4, v7, v6, v4
	v_or3_b32 v2, s2, v22, v21
	s_lshl_b32 s2, s0, 11
	s_add_i32 s3, s1, 0
	v_add_u32_e32 v3, v17, v18
	v_mul_lo_u32 v19, v5, s13
	v_mul_lo_u32 v4, v4, s13
	v_readlane_b32 s98, v248, 52
	s_add_i32 s2, s3, s2
	v_add_lshl_u32 v132, v3, v19, 1
	v_mov_b32_e32 v132, v247
	v_add_lshl_u32 v134, v4, v3, 1
	v_ashrrev_i32_e32 v3, 31, v2
	v_readlane_b32 s99, v248, 53
	s_add_i32 s21, s2, 0x21010
	s_lshl_b32 s16, s13, 8
	s_mov_b32 s17, s81
	v_lshl_add_u64 v[2:3], v[2:3], 4, s[98:99]
	s_mov_b32 m0, s21
	s_lshl_b64 s[70:71], s[16:17], 1
	global_load_lds_dwordx4 v[2:3], off
	s_add_i32 m0, s2, 0x21410
	s_ashr_i32 s2, s18, 31
	s_mul_i32 s2, s70, s2
	s_mul_hi_u32 s3, s70, s18
	s_mov_b64 s[6:7], 0x800
	s_add_i32 s2, s3, s2
	s_bfe_u32 s3, s13, 0x10017
	v_lshl_add_u64 v[2:3], v[2:3], 0, s[6:7]
	s_mul_i32 s6, s3, s18
	s_add_i32 s6, s2, s6
	s_ashr_i32 s2, s80, 31
	s_mul_i32 s2, s70, s2
	s_mul_hi_u32 s9, s70, s80
	s_add_i32 s2, s9, s2
	s_mul_i32 s3, s3, s80
	s_add_i32 s2, s2, s3
	s_mul_i32 s3, s70, s80
	v_readlane_b32 s92, v248, 46
	v_readlane_b32 s93, v248, 47
	s_add_u32 s10, s92, s3
	s_addc_u32 s11, s93, s2
	s_add_i32 s23, s20, 0
	global_load_lds_dwordx4 v[2:3], off
	s_add_i32 m0, s23, 0x10000
	s_mul_i32 s7, s70, s18
	global_load_lds_dwordx4 v0, s[10:11]
	s_add_i32 m0, s23, 0x12000
	s_add_u32 s2, s10, s16
	global_load_lds_dwordx4 v134, s[10:11]
	s_addc_u32 s3, s11, 0
	s_add_i32 m0, s23, 0x14000
	v_mov_b32_e32 v135, v1
	global_load_lds_dwordx4 v0, s[2:3]
	s_add_i32 m0, s23, 0x16000
	v_readlane_b32 s96, v248, 48
	v_lshl_add_u64 v[6:7], s[2:3], 0, v[0:1]
	v_lshl_add_u64 v[8:9], s[2:3], 0, v[134:135]
	global_load_lds_dwordx4 v134, s[2:3]
	v_readlane_b32 s97, v248, 49
	s_add_u32 s2, s96, s7
	s_addc_u32 s3, s97, s6
	s_add_i32 s52, s23, 0x2000
	s_mov_b32 m0, s23
	s_add_u32 s6, s2, s16
	global_load_lds_dwordx4 v130, s[2:3]
	s_mov_b32 m0, s52
	s_addc_u32 s7, s3, 0
	s_add_i32 s53, s23, 0x4000
	global_load_lds_dwordx4 v132, s[2:3]
	s_mov_b32 m0, s53
	s_add_i32 s54, s23, 0x6000
	global_load_lds_dwordx4 v130, s[6:7]
	s_mov_b32 m0, s54
	s_cmp_eq_u32 s8, 1
	global_load_lds_dwordx4 v132, s[6:7]
	v_mov_b32_e32 v131, v1
	v_mov_b32_e32 v133, v1
	s_cselect_b64 s[6:7], -1, 0
	v_lshl_add_u64 v[2:3], s[10:11], 0, v[0:1]
	v_lshl_add_u64 v[4:5], s[10:11], 0, v[134:135]
	v_lshl_add_u64 v[10:11], s[2:3], 0, v[130:131]
	v_lshl_add_u64 v[12:13], s[2:3], 0, v[132:133]
	v_writelane_b32 v248, s6, 29
	s_cmp_lg_u32 s8, 1
	s_nop 0
	v_writelane_b32 v248, s7, 30
	s_cbranch_scc1 .LBB0_349
	s_barrier
.LBB0_349:
	s_add_i32 m0, s23, 0x18000
	v_lshl_add_u64 v[2:3], v[2:3], 0, s[94:95]
	s_waitcnt vmcnt(2)
	s_barrier
	global_load_lds_dwordx4 v[2:3], off
	v_lshl_add_u64 v[2:3], v[4:5], 0, s[94:95]
	s_add_i32 m0, s23, 0x1a000
	s_add_i32 s56, s23, 0x8000
	global_load_lds_dwordx4 v[2:3], off
	v_lshl_add_u64 v[2:3], v[10:11], 0, s[94:95]
	s_mov_b32 m0, s56
	s_add_i32 s57, s23, 0xa000
	global_load_lds_dwordx4 v[2:3], off
	v_lshl_add_u64 v[2:3], v[12:13], 0, s[94:95]
	s_mov_b32 m0, s57
	v_or_b32_e32 v159, s5, v21
	global_load_lds_dwordx4 v[2:3], off
	s_add_i32 m0, s23, 0x1c000
	v_lshl_add_u64 v[2:3], v[6:7], 0, s[94:95]
	global_load_lds_dwordx4 v[2:3], off
	v_lshl_add_u64 v[2:3], v[8:9], 0, s[94:95]
	s_add_i32 m0, s23, 0x1e000
	v_lshlrev_b32_e32 v24, 6, v159
	global_load_lds_dwordx4 v[2:3], off
	s_movk_i32 s5, 0x3c0
	v_lshlrev_b32_e32 v25, 2, v159
	s_lshr_b32 s55, s13, 6
	v_and_or_b32 v24, v24, s5, v22
	v_and_b32_e32 v25, 32, v25
	v_bitop3_b32 v24, v24, s1, v25 bitop3:0xde
	s_lshl_b32 s1, s0, 12
	v_lshlrev_b32_e32 v26, 2, v21
	s_add_i32 s58, s55, -2
	v_lshlrev_b32_e32 v23, 3, v20
	v_lshl_or_b32 v25, v21, 6, v22
	v_and_b32_e32 v26, 32, v26
	s_cmpk_lt_u32 s4, 0x100
	v_or_b32_e32 v2, s0, v20
	v_bitop3_b32 v160, v25, s1, v26 bitop3:0xde
	v_lshl_or_b32 v161, s0, 5, v23
	s_cselect_b64 s[14:15], -1, 0
	s_lshl_b32 s60, s0, 3
	v_cmp_eq_u32_e64 s[0:1], 0, v2
	v_mov_b32_e32 v3, v1
	s_waitcnt vmcnt(6)
	v_or_b32_e32 v164, 16, v159
	v_writelane_b32 v248, s0, 24
	v_or_b32_e32 v165, 32, v159
	v_or_b32_e32 v166, 48, v159
	v_writelane_b32 v248, s1, 25
	v_add_u32_e32 v167, 0x90, v159
	v_readlane_b32 s0, v248, 42
	s_lshl_b32 s62, s0, 2
	v_cvt_f32_u32_e32 v2, s62
	s_sub_i32 s0, 0, s62
	v_add_u32_e32 v168, 0xa0, v159
	v_add_u32_e32 v169, 0xb0, v159
	v_rcp_iflag_f32_e32 v2, v2
	v_lshlrev_b32_e32 v4, 4, v21
	v_add_u32_e32 v163, 0x80, v159
	v_lshlrev_b32_e32 v5, 5, v164
	v_mul_f32_e32 v2, 0x4f7ffffe, v2
	v_cvt_u32_f32_e32 v2, v2
	v_lshlrev_b32_e32 v6, 5, v165
	v_lshlrev_b32_e32 v7, 5, v166
	v_lshlrev_b32_e32 v8, 5, v167
	v_readfirstlane_b32 s1, v2
	v_add_u32_e32 v2, v16, v14
	v_add_lshl_u32 v2, v2, v15, 1
	v_mov_b32_e32 v2, v246
	s_mul_i32 s0, s0, s1
	v_lshl_add_u64 v[136:137], s[16:17], 0, v[2:3]
	v_add_u32_e32 v2, v19, v17
	v_lshlrev_b32_e32 v9, 5, v168
	v_lshlrev_b32_e32 v10, 5, v169
	v_readlane_b32 s6, v249, 46
	s_mul_hi_u32 s0, s1, s0
	v_add_lshl_u32 v2, v2, v18, 1
	v_mov_b32_e32 v2, v247
	v_or_b32_e32 v162, v159, v22
	s_mov_b32 s59, 0
	v_cmp_eq_u32_e64 s[4:5], 0, v20
	s_mov_b32 s13, s81
	s_lshr_b32 s61, s12, 3
	v_lshl_add_u32 v170, v159, 5, s6
	v_lshl_add_u32 v171, v163, 5, s6
	s_add_i32 s63, s1, s0
	v_lshl_add_u64 v[138:139], s[16:17], 0, v[2:3]
	v_add_u32_e32 v172, 0, v24
	v_lshrrev_b32_e32 v245, 10, v172
	v_lshl_or_b32 v172, v245, 10, v243
	v_add_u32_e32 v173, s21, v4
	v_add_u32_e32 v174, s6, v5
	v_add_u32_e32 v175, s6, v6
	v_add_u32_e32 v176, s6, v7
	v_add_u32_e32 v177, s6, v8
	v_add_u32_e32 v178, s6, v9
	v_add_u32_e32 v179, s6, v10
	s_mov_b32 s72, 0x3e6d3388
	s_mov_b32 s90, 0xbf3a00e3
	s_barrier
	s_branch .LBB0_352

.LBB0_406:
	v_bfe_i32 v4, v2, 27, 1
	v_lshlrev_b32_e32 v3, 4, v2
	v_lshrrev_b32_e32 v4, 22, v4
	v_add_u32_e32 v4, v3, v4
	v_and_b32_e32 v4, 0xfffffc00, v4
	v_ashrrev_i32_e32 v0, 31, v2
	v_sub_u32_e32 v4, v3, v4
	v_lshrrev_b32_e32 v0, 26, v0
	v_lshrrev_b32_e32 v5, 4, v4
	v_add_u32_e32 v0, v2, v0
	v_bitop3_b32 v5, v5, v4, 32 bitop3:0x6c
	v_ashrrev_i32_e32 v4, 31, v4
	v_ashrrev_i32_e32 v0, 6, v0
	v_lshrrev_b32_e32 v4, 26, v4
	v_lshlrev_b32_e32 v6, 3, v0
	v_add_u32_e32 v4, v5, v4
	v_and_b32_e32 v6, -16, v6
	v_ashrrev_i32_e32 v4, 6, v4
	v_lshlrev_b32_e32 v0, 5, v0
	v_add_u32_e32 v6, v4, v6
	v_and_b32_e32 v14, 32, v0
	v_mul_i32_i24_e32 v0, 64, v4
	v_sub_u32_e32 v0, v5, v0
	v_lshlrev_b32_e32 v5, 1, v6
	v_lshrrev_b32_e32 v7, 2, v6
	v_and_b32_e32 v4, 3, v4
	s_mov_b32 s2, 0x7fffffe0
	v_ashrrev_i16_sdwa v0, v152, sext(v0) dst_sel:DWORD dst_unused:UNUSED_PAD src0_sel:DWORD src1_sel:BYTE_0
	v_and_b32_e32 v5, 24, v5
	v_and_b32_e32 v7, 4, v7
	v_and_or_b32 v4, v6, s2, v4
	v_bfe_i32 v16, v0, 0, 16
	v_or3_b32 v4, v4, v7, v5
	v_readlane_b32 s15, v248, 43
	v_add_u32_e32 v0, v14, v16
	v_add_u32_e32 v3, 0x2000, v3
	v_mul_lo_u32 v17, v6, s15
	v_mul_lo_u32 v4, v4, s15
	v_add_lshl_u32 v130, v0, v17, 1
	v_and_b32_e32 v240, 63, v150
	v_lshrrev_b32_e32 v241, 4, v240
	v_bfe_u32 v242, v240, 2, 2
	v_sub_u32_e32 v243, 0, v241
	v_and_b32_e32 v243, 3, v243
	v_xor_b32_e32 v242, v242, v243
	v_lshl_or_b32 v241, v241, 2, v242
	v_lshrrev_b32_e32 v243, 7, v150
	v_lshl_or_b32 v241, v243, 4, v241
	v_and_b32_e32 v242, 3, v240
	v_lshlrev_b32_e32 v242, 3, v242
	v_mul_lo_u32 v244, v241, s15
	v_add3_u32 v246, v244, v14, v242
	v_lshlrev_b32_e32 v246, 1, v246
	v_lshl_add_u32 v247, s15, 7, v246
	v_mov_b32_e32 v130, v246
	v_and_b32_e32 v240, 15, v150
	v_bfe_u32 v243, v150, 4, 2
	v_lshrrev_b32_e32 v244, 2, v240
	v_sub_u32_e32 v245, 0, v244
	v_and_b32_e32 v245, 3, v245
	v_xor_b32_e32 v243, v243, v245
	v_lshlrev_b32_e32 v244, 8, v244
	v_lshl_or_b32 v243, v243, 6, v244
	v_and_b32_e32 v240, 3, v240
	v_lshl_or_b32 v243, v240, 4, v243
	v_add_lshl_u32 v0, v4, v0, 1
	v_ashrrev_i32_e32 v4, 31, v3
	v_lshrrev_b32_e32 v4, 22, v4
	v_add_u32_e32 v4, v3, v4
	v_ashrrev_i32_e32 v4, 10, v4
	v_mul_i32_i24_e32 v5, 0x400, v4
	v_sub_u32_e32 v3, v3, v5
	v_lshrrev_b32_e32 v5, 4, v3
	v_bitop3_b32 v3, v5, v3, 32 bitop3:0x6c
	v_ashrrev_i32_e32 v6, 31, v3
	v_lshrrev_b32_e32 v6, 26, v6
	v_lshlrev_b32_e32 v5, 3, v4
	v_add_u32_e32 v6, v3, v6
	v_and_b32_e32 v5, -16, v5
	v_ashrrev_i32_e32 v7, 6, v6
	v_lshlrev_b32_e32 v4, 5, v4
	v_add_u32_e32 v5, v7, v5
	v_and_b32_e32 v18, 32, v4
	v_and_b32_e32 v4, 0xc0, v6
	s_ashr_i32 s13, s0, 8
	s_ashr_i32 s6, s0, 6
	v_bfe_u32 v15, v2, 4, 2
	v_sub_u32_e32 v3, v3, v4
	v_lshlrev_b32_e32 v4, 1, v5
	v_lshrrev_b32_e32 v6, 2, v5
	v_and_b32_e32 v7, 3, v7
	s_lshl_b32 s7, s13, 6
	s_lshl_b32 s8, s62, 8
	s_sext_i32_i16 s63, s1
	s_and_b32 s1, s6, 3
	v_ashrrev_i16_sdwa v3, v152, sext(v3) dst_sel:DWORD dst_unused:UNUSED_PAD src0_sel:DWORD src1_sel:BYTE_0
	v_and_b32_e32 v4, 24, v4
	v_and_b32_e32 v6, 4, v6
	v_and_or_b32 v7, v5, s2, v7
	v_and_b32_e32 v21, 15, v2
	s_lshl_b32 s30, s6, 10
	v_lshlrev_b32_e32 v22, 4, v15
	s_lshl_b32 s6, s13, 13
	s_add_i32 s8, s8, s7
	v_bfe_i32 v19, v3, 0, 16
	v_or3_b32 v4, v7, v6, v4
	v_or3_b32 v2, s8, v22, v21
	s_lshl_b32 s8, s1, 11
	s_add_i32 s9, s6, 0
	v_readlane_b32 s96, v248, 52
	v_add_u32_e32 v3, v18, v19
	v_mul_lo_u32 v20, v5, s15
	v_mul_lo_u32 v4, v4, s15
	s_add_i32 s8, s9, s8
	v_readlane_b32 s97, v248, 53
	v_add_lshl_u32 v132, v3, v20, 1
	v_mov_b32_e32 v132, v247
	v_add_lshl_u32 v134, v4, v3, 1
	v_ashrrev_i32_e32 v3, 31, v2
	s_add_i32 s31, s8, 0x21010
	s_lshl_b32 s80, s15, 8
	v_lshl_add_u64 v[2:3], v[2:3], 4, s[96:97]
	s_mov_b32 m0, s31
	s_lshl_b64 s[2:3], s[80:81], 1
	global_load_lds_dwordx4 v[2:3], off
	s_add_i32 m0, s8, 0x21410
	s_ashr_i32 s8, s62, 31
	s_mul_i32 s8, s2, s8
	s_mul_hi_u32 s9, s2, s62
	s_add_i32 s8, s9, s8
	s_bfe_u32 s9, s15, 0x10017
	s_mul_i32 s10, s9, s62
	s_add_i32 s10, s8, s10
	s_ashr_i32 s8, s63, 31
	s_mul_i32 s8, s2, s8
	s_mul_hi_u32 s14, s2, s63
	s_add_i32 s8, s14, s8
	s_mul_i32 s9, s9, s63
	v_readlane_b32 s90, v248, 46
	s_add_i32 s8, s8, s9
	s_mul_i32 s9, s2, s63
	v_readlane_b32 s91, v248, 47
	s_add_u32 s20, s90, s9
	v_lshl_add_u64 v[2:3], v[2:3], 0, s[82:83]
	s_addc_u32 s21, s91, s8
	s_add_i32 s35, s30, 0
	global_load_lds_dwordx4 v[2:3], off
	s_add_i32 m0, s35, 0x10000
	v_readlane_b32 s92, v248, 48
	global_load_lds_dwordx4 v0, s[20:21]
	s_add_i32 m0, s35, 0x12000
	s_add_u32 s8, s20, s80
	global_load_lds_dwordx4 v134, s[20:21]
	s_addc_u32 s9, s21, 0
	s_add_i32 m0, s35, 0x14000
	s_mul_i32 s11, s2, s62
	global_load_lds_dwordx4 v0, s[8:9]
	s_add_i32 m0, s35, 0x16000
	v_readlane_b32 s93, v248, 49
	s_add_u32 s16, s92, s11
	s_addc_u32 s17, s93, s10
	s_add_i32 s52, s35, 0x2000
	global_load_lds_dwordx4 v134, s[8:9]
	s_mov_b32 m0, s35
	s_add_u32 s10, s16, s80
	global_load_lds_dwordx4 v130, s[16:17]
	s_mov_b32 m0, s52
	s_addc_u32 s11, s17, 0
	s_add_i32 s53, s35, 0x4000
	global_load_lds_dwordx4 v132, s[16:17]
	s_mov_b32 m0, s53
	s_add_i32 s54, s35, 0x6000
	global_load_lds_dwordx4 v130, s[10:11]
	s_mov_b32 m0, s54
	v_mov_b32_e32 v135, v1
	global_load_lds_dwordx4 v132, s[10:11]
	v_mov_b32_e32 v131, v1
	v_mov_b32_e32 v133, v1
	s_cmp_eq_u32 s13, 1
	v_lshl_add_u64 v[10:11], s[20:21], 0, v[0:1]
	v_lshl_add_u64 v[6:7], s[20:21], 0, v[134:135]
	v_lshl_add_u64 v[4:5], s[8:9], 0, v[0:1]
	v_lshl_add_u64 v[2:3], s[8:9], 0, v[134:135]
	v_lshl_add_u64 v[8:9], s[16:17], 0, v[130:131]
	s_cselect_b64 s[8:9], -1, 0
	s_cmp_lg_u32 s13, 1
	v_lshl_add_u64 v[12:13], s[16:17], 0, v[132:133]
	v_readlane_b32 s73, v250, 31
	s_cbranch_scc1 .LBB0_408
	s_barrier
.LBB0_408:
	s_add_i32 m0, s35, 0x18000
	v_lshl_add_u64 v[10:11], v[10:11], 0, s[94:95]
	s_waitcnt vmcnt(2)
	s_barrier
	global_load_lds_dwordx4 v[10:11], off
	v_lshl_add_u64 v[6:7], v[6:7], 0, s[94:95]
	s_add_i32 m0, s35, 0x1a000
	s_add_i32 s55, s35, 0x8000
	global_load_lds_dwordx4 v[6:7], off
	v_lshl_add_u64 v[6:7], v[8:9], 0, s[94:95]
	s_mov_b32 m0, s55
	s_add_i32 s56, s35, 0xa000
	global_load_lds_dwordx4 v[6:7], off
	v_lshl_add_u64 v[6:7], v[12:13], 0, s[94:95]
	s_mov_b32 m0, s56
	v_lshl_add_u64 v[4:5], v[4:5], 0, s[94:95]
	global_load_lds_dwordx4 v[6:7], off
	s_add_i32 m0, s35, 0x1c000
	v_lshl_add_u64 v[2:3], v[2:3], 0, s[94:95]
	global_load_lds_dwordx4 v[4:5], off
	s_add_i32 m0, s35, 0x1e000
	v_or_b32_e32 v142, s7, v21
	global_load_lds_dwordx4 v[2:3], off
	v_lshlrev_b32_e32 v3, 6, v142
	s_movk_i32 s7, 0x3c0
	v_lshlrev_b32_e32 v4, 2, v142
	v_lshlrev_b32_e32 v2, 3, v15
	v_and_or_b32 v3, v3, s7, v22
	v_and_b32_e32 v4, 32, v4
	v_lshlrev_b32_e32 v5, 2, v21
	v_bitop3_b32 v4, v3, s6, v4 bitop3:0xde
	v_lshl_or_b32 v3, v21, 6, v22
	s_lshl_b32 s6, s1, 12
	v_and_b32_e32 v5, 32, v5
	v_lshl_or_b32 v144, s1, 5, v2
	v_add_u32_e32 v2, v17, v14
	s_lshr_b32 s57, s15, 6
	v_bitop3_b32 v143, v3, s6, v5 bitop3:0xde
	v_add_lshl_u32 v2, v2, v16, 1
	v_mov_b32_e32 v2, v246
	v_mov_b32_e32 v3, v1
	s_waitcnt vmcnt(6)
	s_add_i32 s58, s57, -2
	v_lshl_add_u64 v[136:137], s[80:81], 0, v[2:3]
	v_add_u32_e32 v2, v20, v18
	s_cmpk_lt_u32 s0, 0x100
	v_lshlrev_b32_e32 v5, 4, v21
	v_add_lshl_u32 v2, v2, v19, 1
	v_mov_b32_e32 v2, v247
	v_or_b32_e32 v145, v142, v22
	s_cselect_b64 s[10:11], -1, 0
	s_mov_b32 s13, s81
	v_lshl_add_u64 v[138:139], s[80:81], 0, v[2:3]
	s_mov_b32 s59, 0
	v_add_u32_e32 v146, 0, v4
	v_lshrrev_b32_e32 v245, 10, v146
	v_lshl_or_b32 v146, v245, 10, v243
	v_add_u32_e32 v147, s31, v5
	s_barrier
	s_branch .LBB0_411

.LBB0_545:
	s_or_b64 exec, exec, s[0:1]
	v_mov_b32_e32 v0, v150
	v_readlane_b32 s0, v250, 4
	v_ashrrev_i32_e32 v2, 6, v0
	s_nop 0
	v_add_u32_e32 v2, s0, v2
	s_mov_b32 s0, 0xc000
	v_cmp_gt_i32_e32 vcc, s0, v2
	s_and_saveexec_b64 s[2:3], vcc
	s_cbranch_execz .LBB0_7
	v_and_b32_e32 v6, 64, v158
	v_add_u32_e32 v6, 64, v6
	v_xor_b32_e32 v7, 32, v158
	v_cmp_lt_i32_e32 vcc, v7, v6
	v_and_b32_e32 v3, 63, v0
	v_readlane_b32 s0, v251, 7
	v_cndmask_b32_e32 v7, v158, v7, vcc
	v_lshlrev_b32_e32 v16, 2, v7
	v_xor_b32_e32 v7, 16, v158
	v_cmp_lt_i32_e32 vcc, v7, v6
	v_bfe_u32 v4, v3, 1, 2
	v_lshlrev_b32_e32 v4, 11, v4
	v_lshrrev_b32_e32 v5, 3, v3
	v_lshl_or_b32 v4, v5, 6, v4
	v_and_b32_e32 v5, 1, v3
	v_lshl_or_b32 v4, v5, 3, v4
	v_mov_b32_e32 v5, v1
	v_cndmask_b32_e32 v7, v158, v7, vcc
	v_lshlrev_b32_e32 v17, 2, v7
	v_xor_b32_e32 v7, 8, v158
	v_cmp_lt_i32_e32 vcc, v7, v6
	v_readlane_b32 s1, v251, 8
	v_lshlrev_b32_e32 v0, 2, v3
	v_cndmask_b32_e32 v7, v158, v7, vcc
	v_lshlrev_b32_e32 v18, 2, v7
	v_xor_b32_e32 v7, 4, v158
	v_cmp_lt_i32_e32 vcc, v7, v6
	v_lshl_add_u64 v[4:5], s[0:1], 0, v[4:5]
	v_readlane_b32 s0, v251, 11
	v_cndmask_b32_e32 v7, v158, v7, vcc
	v_lshlrev_b32_e32 v19, 2, v7
	v_xor_b32_e32 v7, 2, v158
	v_cmp_lt_i32_e32 vcc, v7, v6
	v_cmp_eq_u32_e64 s[4:5], 0, v3
	v_readlane_b32 s1, v251, 12
	v_cndmask_b32_e32 v7, v158, v7, vcc
	v_lshlrev_b32_e32 v20, 2, v7
	v_xor_b32_e32 v7, 1, v158
	v_cmp_lt_i32_e32 vcc, v7, v6
	s_mov_b64 s[6:7], 0
	s_nop 0
	v_cndmask_b32_e32 v6, v158, v7, vcc
	v_cmp_gt_u32_e32 vcc, 4, v3
	v_ashrrev_i32_e32 v3, 31, v2
	v_lshlrev_b64 v[8:9], 12, v[2:3]
	v_lshlrev_b32_e32 v21, 2, v6
	v_lshl_add_u64 v[6:7], s[0:1], 0, v[0:1]
	v_lshl_add_u64 v[8:9], s[36:37], 0, v[8:9]
	v_lshlrev_b32_e32 v0, 2, v0
	s_branch .LBB0_548

.LBB0_548:
	v_cmp_lt_i32_e64 s[0:1], s87, v2
	v_mov_b64_e32 v[10:11], v[2:3]
	s_waitcnt lgkmcnt(0)
	v_mov_b64_e32 v[12:13], v[8:9]
	s_and_saveexec_b64 s[8:9], s[0:1]
	v_add_u32_e32 v10, 0xffff8000, v2
	v_mov_b32_e32 v11, v1
	v_lshlrev_b64 v[10:11], 12, v[10:11]
	v_lshl_add_u64 v[12:13], s[38:39], 0, v[10:11]
	v_mov_b32_e32 v10, v2
	v_mov_b32_e32 v11, v1
	s_or_b64 exec, exec, s[8:9]
	v_lshl_add_u64 v[14:15], v[12:13], 0, v[0:1]
	v_and_b32_e32 v26, 3, v10
	v_lshlrev_b32_e32 v26, 4, v26
	v_mov_b32_e32 v27, 0
	v_and_b32_e32 v12, -4, v10
	v_mov_b32_e32 v13, v11
	v_lshlrev_b64 v[12:13], 11, v[12:13]
	v_lshl_add_u64 v[12:13], v[12:13], 0, v[26:27]
	v_lshl_add_u64 v[12:13], v[4:5], 0, v[12:13]
	global_load_dwordx4 v[22:25], v[14:15], off
	global_load_dwordx4 v[30:33], v[14:15], off offset:1024
	global_load_dwordx4 v[34:37], v[14:15], off offset:2048
	global_load_dwordx4 v[38:41], v[14:15], off offset:3072
	s_waitcnt vmcnt(3)
	v_mul_f32_e32 v26, v23, v23
	v_fmac_f32_e32 v26, v22, v22
	v_and_b32_sdwa v27, v24, v152 dst_sel:DWORD dst_unused:UNUSED_PAD src0_sel:WORD_1 src1_sel:DWORD
	v_and_b32_sdwa v28, v22, v152 dst_sel:DWORD dst_unused:UNUSED_PAD src0_sel:WORD_1 src1_sel:DWORD
	v_fmac_f32_e32 v26, v24, v24
	v_add3_u32 v22, v22, v28, s87
	v_add3_u32 v24, v24, v27, s87
	v_and_b32_sdwa v27, v25, v152 dst_sel:DWORD dst_unused:UNUSED_PAD src0_sel:WORD_1 src1_sel:DWORD
	v_and_b32_sdwa v28, v23, v152 dst_sel:DWORD dst_unused:UNUSED_PAD src0_sel:WORD_1 src1_sel:DWORD
	v_fmac_f32_e32 v26, v25, v25
	v_add3_u32 v25, v25, v27, s87
	v_add3_u32 v23, v23, v28, s87
	v_and_b32_e32 v25, 0xffff0000, v25
	v_and_b32_e32 v27, 0xffff0000, v23
	v_or_b32_sdwa v23, v25, v24 dst_sel:DWORD dst_unused:UNUSED_PAD src0_sel:DWORD src1_sel:WORD_1
	v_or_b32_sdwa v22, v27, v22 dst_sel:DWORD dst_unused:UNUSED_PAD src0_sel:DWORD src1_sel:WORD_1
	global_store_dwordx2 v[12:13], v[22:23], off
	s_waitcnt vmcnt(3)
	v_mul_f32_e32 v27, v31, v31
	v_fmac_f32_e32 v27, v30, v30
	v_fmac_f32_e32 v27, v32, v32
	v_fmac_f32_e32 v27, v33, v33
	v_add_f32_e32 v26, v26, v27
	v_and_b32_sdwa v27, v32, v152 dst_sel:DWORD dst_unused:UNUSED_PAD src0_sel:WORD_1 src1_sel:DWORD
	v_and_b32_sdwa v28, v30, v152 dst_sel:DWORD dst_unused:UNUSED_PAD src0_sel:WORD_1 src1_sel:DWORD
	v_add3_u32 v30, v30, v28, s87
	v_add3_u32 v32, v32, v27, s87
	v_and_b32_sdwa v27, v33, v152 dst_sel:DWORD dst_unused:UNUSED_PAD src0_sel:WORD_1 src1_sel:DWORD
	v_and_b32_sdwa v28, v31, v152 dst_sel:DWORD dst_unused:UNUSED_PAD src0_sel:WORD_1 src1_sel:DWORD
	v_add3_u32 v33, v33, v27, s87
	v_add3_u32 v31, v31, v28, s87
	v_and_b32_e32 v33, 0xffff0000, v33
	v_and_b32_e32 v27, 0xffff0000, v31
	v_or_b32_sdwa v31, v33, v32 dst_sel:DWORD dst_unused:UNUSED_PAD src0_sel:DWORD src1_sel:WORD_1
	v_or_b32_sdwa v30, v27, v30 dst_sel:DWORD dst_unused:UNUSED_PAD src0_sel:DWORD src1_sel:WORD_1
	global_store_dwordx2 v[12:13], v[30:31], off offset:512
	s_waitcnt vmcnt(3)
	v_mul_f32_e32 v27, v35, v35
	v_fmac_f32_e32 v27, v34, v34
	v_fmac_f32_e32 v27, v36, v36
	v_fmac_f32_e32 v27, v37, v37
	v_add_f32_e32 v26, v26, v27
	v_and_b32_sdwa v27, v36, v152 dst_sel:DWORD dst_unused:UNUSED_PAD src0_sel:WORD_1 src1_sel:DWORD
	v_and_b32_sdwa v28, v34, v152 dst_sel:DWORD dst_unused:UNUSED_PAD src0_sel:WORD_1 src1_sel:DWORD
	v_add3_u32 v34, v34, v28, s87
	v_add3_u32 v36, v36, v27, s87
	v_and_b32_sdwa v27, v37, v152 dst_sel:DWORD dst_unused:UNUSED_PAD src0_sel:WORD_1 src1_sel:DWORD
	v_and_b32_sdwa v28, v35, v152 dst_sel:DWORD dst_unused:UNUSED_PAD src0_sel:WORD_1 src1_sel:DWORD
	v_add3_u32 v37, v37, v27, s87
	v_add3_u32 v35, v35, v28, s87
	v_and_b32_e32 v37, 0xffff0000, v37
	v_and_b32_e32 v27, 0xffff0000, v35
	v_or_b32_sdwa v35, v37, v36 dst_sel:DWORD dst_unused:UNUSED_PAD src0_sel:DWORD src1_sel:WORD_1
	v_or_b32_sdwa v34, v27, v34 dst_sel:DWORD dst_unused:UNUSED_PAD src0_sel:DWORD src1_sel:WORD_1
	global_store_dwordx2 v[12:13], v[34:35], off offset:1024
	s_waitcnt vmcnt(3)
	v_mul_f32_e32 v14, v39, v39
	v_fmac_f32_e32 v14, v38, v38
	v_fmac_f32_e32 v14, v40, v40
	v_fmac_f32_e32 v14, v41, v41
	v_add_f32_e32 v26, v26, v14
	v_and_b32_sdwa v14, v40, v152 dst_sel:DWORD dst_unused:UNUSED_PAD src0_sel:WORD_1 src1_sel:DWORD
	v_and_b32_sdwa v15, v38, v152 dst_sel:DWORD dst_unused:UNUSED_PAD src0_sel:WORD_1 src1_sel:DWORD
	v_add3_u32 v38, v38, v15, s87
	v_add3_u32 v14, v40, v14, s87
	v_and_b32_sdwa v15, v41, v152 dst_sel:DWORD dst_unused:UNUSED_PAD src0_sel:WORD_1 src1_sel:DWORD
	v_and_b32_sdwa v40, v39, v152 dst_sel:DWORD dst_unused:UNUSED_PAD src0_sel:WORD_1 src1_sel:DWORD
	v_add3_u32 v15, v41, v15, s87
	v_add3_u32 v39, v39, v40, s87
	v_and_b32_e32 v15, 0xffff0000, v15
	v_and_b32_e32 v39, 0xffff0000, v39
	v_or_b32_sdwa v15, v15, v14 dst_sel:DWORD dst_unused:UNUSED_PAD src0_sel:DWORD src1_sel:WORD_1
	v_or_b32_sdwa v14, v39, v38 dst_sel:DWORD dst_unused:UNUSED_PAD src0_sel:DWORD src1_sel:WORD_1
	global_store_dwordx2 v[12:13], v[14:15], off offset:1536
	ds_bpermute_b32 v12, v16, v26
	s_waitcnt lgkmcnt(0)
	v_add_f32_e32 v12, v26, v12
	ds_bpermute_b32 v13, v17, v12
	s_waitcnt lgkmcnt(0)
	v_add_f32_e32 v12, v12, v13
	ds_bpermute_b32 v13, v18, v12
	s_waitcnt lgkmcnt(0)
	v_add_f32_e32 v12, v12, v13
	ds_bpermute_b32 v13, v19, v12
	s_waitcnt lgkmcnt(0)
	v_add_f32_e32 v12, v12, v13
	ds_bpermute_b32 v13, v20, v12
	s_waitcnt lgkmcnt(0)
	v_add_f32_e32 v12, v12, v13
	ds_bpermute_b32 v13, v21, v12
	s_and_saveexec_b64 s[0:1], vcc
	s_cbranch_execz .LBB0_547
	s_waitcnt lgkmcnt(0)
	v_add_f32_e32 v12, v12, v13
	v_cndmask_b32_e64 v12, 0, v12, s[4:5]
	v_lshl_add_u64 v[10:11], v[10:11], 4, v[6:7]
	global_store_dword v[10:11], v12, off
	s_branch .LBB0_547
